# SGU unit rewritten: all 25 global loads of a unit issued up front (one exposed memory round trip instead of ~12), queue atomic consumed at unit end, two redundant barriers per unit dropped
# baseline (speedup 1.0000x reference)
; #define LAS __attribute__((address_space(3)))
; __device__ __forceinline__ void sgu_unit(ldsp lds, const bf16* proj, bf16* mix, const float* sgup, const float* ln_g, const float* ln_b, const float* w_s, const float* b_s, int unit, int tid) {
;     ...
;     const int g = unit & 7, n = (unit >> 3) & 31, b = unit >> 8;
;     const ldsp TA = lds, TB = lds + TILE_BYTES;
;     LAS float* stat = (LAS float*)(lds + 3 * TILE_BYTES);
;     const size_t row0 = (size_t)b * SEQ + (size_t)n * CHUNK;
;     ...
;     TileRegs rv; tile_fetch(rv, proj + row0 * INW + C_V + g * HDIM, INW, tid);
;     v4u ur[4];
;     { const bf16* ub = proj + (row0 + 16 * w) * INW + C_U + g * HDIM;
; #pragma unroll
;       for (int k = 0; k < 4; ++k) { const int q = lane + 64 * k; ur[k] = *(const v4u*)(ub + (size_t)(q >> 4) * INW + 8 * (q & 15)); } }
;     f32x4 wx[4], wy[4];
;     { const float* wsp = w_s + (size_t)g * CHUNK * CHUNK;
; #pragma unroll
;       for (int i = 0; i < 4; ++i) { const int ck = tid + 512 * i, r = ck >> 4, ch = ck & 15; wx[i] = *(const f32x4*)(wsp + r * 128 + 8 * ch); wy[i] = *(const f32x4*)(wsp + r * 128 + 8 * ch + 4); } }
;     ...
;     __syncthreads();
;     { const int tok = tid >> 2, q = tid & 3;
;       const f32x4* p = (const f32x4*)(sgup + ((row0 + tok) * 16 + 4 * q) * 2);
;       const f32x4 a = p[0], c = p[1];
;       float s = (a[0] + a[2]) + (c[0] + c[2]), ss = (a[1] + a[3]) + (c[1] + c[3]);
;       s += __shfl_xor(s, 1); ss += __shfl_xor(ss, 1); s += __shfl_xor(s, 2); ss += __shfl_xor(ss, 2);
;       const float mean = s * (1.f / 1024.f), var = fmaxf(ss * (1.f / 1024.f) - mean * mean, 0.f);
;       if (q == 0) { stat[2 * tok] = mean; stat[2 * tok + 1] = rsqrtf(var + NORM_EPS); } }
;     const float* ws = w_s + (size_t)g * CHUNK * CHUNK;
; #pragma unroll
;     for (int i = 0; i < 4; ++i) { const int ck = tid + 512 * i, r = ck >> 4, ch = ck & 15;
;     ...
;         const f32x4 x = wx[i], y = wy[i];
;     ...
;         const f32x4 x = *(const f32x4*)(ws + r * 128 + 8 * ch), y = *(const f32x4*)(ws + r * 128 + 8 * ch + 4);
;     ...
;         v4u v; v[0] = cvt_pk_bf16(x[0], x[1]); v[1] = cvt_pk_bf16(x[2], x[3]); v[2] = cvt_pk_bf16(y[0], y[1]); v[3] = cvt_pk_bf16(y[2], y[3]);
;         *(LAS v4u*)(TA + offb(r, ch)) = v; }
;     ...
;     TileRegs rv; tile_fetch(rv, proj + row0 * INW + C_V + g * HDIM, INW, tid);
.LBB0_398:
	v_mov_b32_e32 v78, 0
	s_and_saveexec_b64 s[0:1], s[6:7]
	s_cbranch_execz .Lsgu_noatom
	v_mov_b32_e32 v78, 1
	global_atomic_add v78, v17, v78, s[20:21] offset:512 sc0
.Lsgu_noatom:
	s_or_b64 exec, exec, s[0:1]
	s_ashr_i32 s0, s16, 8
	s_ashr_i32 s1, s0, 31
	s_lshl_b64 s[22:23], s[0:1], 12
	s_lshl_b32 s0, s16, 4
	s_and_b32 s0, s0, 0xf80
	s_or_b32 s22, s22, s0
	v_lshl_add_u64 v[0:1], s[22:23], 0, v[12:13]
	v_readfirstlane_b32 s4, v21
	v_lshlrev_b64 v[0:1], 7, v[0:1]
	s_and_b32 s0, s16, 7
	v_lshl_add_u64 v[0:1], v[14:15], 0, v[0:1]
	s_lshl_b32 s78, s0, 16
	global_load_dwordx4 v[4:7], v[0:1], off
	global_load_dwordx4 v[8:11], v[0:1], off offset:16
	v_lshl_add_u64 v[2:3], v[18:19], 0, s[78:79]
	v_lshl_add_u64 v[0:1], v[22:23], 2, v[2:3]
	global_load_dwordx4 v[178:181], v[0:1], off
	global_load_dwordx4 v[182:185], v[0:1], off offset:16
	v_lshl_add_u64 v[0:1], v[24:25], 2, v[2:3]
	global_load_dwordx4 v[186:189], v[0:1], off
	global_load_dwordx4 v[190:193], v[0:1], off offset:16
	v_lshl_add_u64 v[0:1], v[26:27], 2, v[2:3]
	global_load_dwordx4 v[194:197], v[0:1], off
	global_load_dwordx4 v[198:201], v[0:1], off offset:16
	v_lshl_add_u64 v[0:1], v[28:29], 2, v[2:3]
	global_load_dwordx4 v[202:205], v[0:1], off
	global_load_dwordx4 v[206:209], v[0:1], off offset:16
	s_ashr_i32 s1, s4, 6
	s_mul_i32 s4, s23, 0x4800
	s_mul_hi_u32 s5, s22, 0x4800
	s_add_i32 s5, s5, s4
	s_mul_i32 s4, s22, 0x4800
	s_add_u32 s12, s58, s4
	s_addc_u32 s5, s59, s5
	s_lshl_b32 s25, s0, 8
	s_add_u32 s12, s12, s25
	s_addc_u32 s13, s5, 0
	v_lshl_add_u64 v[0:1], s[12:13], 0, v[16:17]
	v_lshl_add_u64 v[2:3], v[0:1], 0, v[30:31]
	global_load_dwordx4 v[80:83], v[2:3], off offset:2048
	v_lshl_add_u64 v[2:3], v[0:1], 0, v[32:33]
	global_load_dwordx4 v[84:87], v[2:3], off offset:2048
	v_lshl_add_u64 v[2:3], v[0:1], 0, v[34:35]
	global_load_dwordx4 v[88:91], v[2:3], off offset:2048
	v_lshl_add_u64 v[2:3], v[0:1], 0, v[36:37]
	global_load_dwordx4 v[92:95], v[2:3], off offset:2048
	s_lshl_b32 s78, s0, 9
	v_lshl_add_u64 v[0:1], v[38:39], 0, s[78:79]
	global_load_dwordx4 v[212:215], v[0:1], off
	global_load_dwordx4 v[216:219], v[0:1], off offset:16
	v_lshl_add_u64 v[2:3], v[40:41], 0, s[78:79]
	global_load_dwordx4 v[220:223], v[2:3], off
	global_load_dwordx4 v[124:127], v[2:3], off offset:16
	s_lshl_b32 s24, s1, 4
	s_lshl_b32 s4, s0, 7
	s_add_i32 s4, s4, s24
	v_add_u32_e32 v0, s4, v62
	v_mov_b32_e32 v1, 0
	v_lshl_add_u64 v[0:1], v[0:1], 2, s[10:11]
	global_load_dword v110, v[0:1], off
	s_add_u32 s12, s22, s24
	s_addc_u32 s13, s23, 0
	s_mul_i32 s4, s13, 0x4800
	s_mul_hi_u32 s5, s12, 0x4800
	s_add_i32 s5, s5, s4
	s_mul_i32 s4, s12, 0x4800
	s_add_u32 s4, s58, s4
	s_addc_u32 s5, s59, s5
	s_add_u32 s22, s4, s25
	s_addc_u32 s23, s5, 0
	v_mov_b32_e32 v61, 0
	v_lshl_add_u64 v[2:3], s[22:23], 0, v[60:61]
	v_lshl_add_u64 v[0:1], v[2:3], 0, v[44:45]
	global_load_dwordx4 v[100:103], v[0:1], off
	v_lshl_add_u64 v[0:1], v[2:3], 0, v[48:49]
	global_load_dwordx4 v[236:239], v[0:1], off
	v_lshl_add_u64 v[0:1], v[2:3], 0, v[52:53]
	global_load_dwordx2 v[224:225], v[0:1], off
	global_load_dwordx2 v[242:243], v[0:1], off offset:8
	v_lshl_add_u64 v[2:3], v[2:3], 0, v[56:57]
	global_load_dwordx2 v[246:247], v[2:3], off
	global_load_dwordx2 v[250:251], v[2:3], off offset:8
	s_waitcnt vmcnt(23)
	v_pk_add_f32 v[4:5], v[4:5], v[6:7]
	v_pk_add_f32 v[8:9], v[8:9], v[10:11]
	s_nop 0
	v_pk_add_f32 v[4:5], v[4:5], v[8:9]
	s_nop 0
	ds_bpermute_b32 v6, v244, v4
	ds_bpermute_b32 v7, v244, v5
	s_waitcnt lgkmcnt(0)
	v_pk_add_f32 v[4:5], v[4:5], v[6:7]
	s_nop 0
	ds_bpermute_b32 v6, v43, v4
	ds_bpermute_b32 v7, v43, v5
	s_and_saveexec_b64 s[4:5], s[8:9]
	s_cbranch_execz .Lsgu_stat
	s_waitcnt lgkmcnt(0)
	v_pk_add_f32 v[4:5], v[4:5], v[6:7]
	s_mov_b32 s22, 0x3a800000
	v_pk_mul_f32 v[4:5], v[4:5], s[22:23] op_sel_hi:[1,0]
	s_mov_b32 s25, 0x800000
	v_fma_f32 v5, -v4, v4, v5
	v_max_f32_e32 v5, 0, v5
	v_add_f32_e32 v5, 0x3727c5ac, v5
	v_mul_f32_e32 v6, 0x4b800000, v5
	v_cmp_gt_f32_e32 vcc, s25, v5
	s_nop 1
	v_cndmask_b32_e32 v5, v5, v6, vcc
	v_rsq_f32_e32 v5, v5
	s_nop 0
	v_mul_f32_e32 v6, 0x45800000, v5
	v_cndmask_b32_e32 v5, v5, v6, vcc
	ds_write_b64 v69, v[4:5]
.Lsgu_stat:
	s_or_b64 exec, exec, s[4:5]
	s_waitcnt vmcnt(21)
	v_cvt_pk_bf16_f32 v178, v178, v179
	v_cvt_pk_bf16_f32 v179, v180, v181
	v_cvt_pk_bf16_f32 v180, v182, v183
	v_cvt_pk_bf16_f32 v181, v184, v185
	ds_write_b128 v70, v[178:181]
	s_waitcnt vmcnt(19)
	v_cvt_pk_bf16_f32 v186, v186, v187
	v_cvt_pk_bf16_f32 v187, v188, v189
	v_cvt_pk_bf16_f32 v188, v190, v191
	v_cvt_pk_bf16_f32 v189, v192, v193
	ds_write_b128 v71, v[186:189]
	s_waitcnt vmcnt(17)
	v_cvt_pk_bf16_f32 v194, v194, v195
	v_cvt_pk_bf16_f32 v195, v196, v197
	v_cvt_pk_bf16_f32 v196, v198, v199
	v_cvt_pk_bf16_f32 v197, v200, v201
	ds_write_b128 v72, v[194:197]
	s_waitcnt vmcnt(15)
	v_cvt_pk_bf16_f32 v202, v202, v203
	v_cvt_pk_bf16_f32 v203, v204, v205
	v_cvt_pk_bf16_f32 v204, v206, v207
	v_cvt_pk_bf16_f32 v205, v208, v209
	ds_write_b128 v73, v[202:205]
	s_mul_i32 s5, s1, 0x1100
	v_add_u32_e32 v61, s5, v63
	s_waitcnt lgkmcnt(0)
	s_barrier
; __device__ __forceinline__ unsigned cvt_pk_bf16(float lo, float hi) { const f32x2c_t v = {lo, hi}; return __builtin_bit_cast(unsigned, __builtin_convertvector(v, bf16x2c_t)); }
; #define LAS __attribute__((address_space(3)))
; __device__ __forceinline__ float bf_lo(unsigned w) { return __uint_as_float(w << 16); }
; __device__ __forceinline__ float bf_hi(unsigned w) { return __uint_as_float(w & 0xffff0000u); }
; __device__ __forceinline__ void sgu_unit(ldsp lds, const bf16* proj, bf16* mix, const float* sgup, const float* ln_g, const float* ln_b, const float* w_s, const float* b_s, int unit, int tid) {
;     ...
;     __syncthreads();
; #pragma unroll
;     for (int i = 0; i < 4; ++i) { const int ck = tid + 512 * i, r = ck >> 4, ch = ck & 15;
;         const v4u v = rv.v[i];
;         const float mean = stat[2 * r], rstd = stat[2 * r + 1];
;         const f32x4 g0 = *(const f32x4*)(ln_g + g * HDIM + 8 * ch), g1 = *(const f32x4*)(ln_g + g * HDIM + 8 * ch + 4);
;         const f32x4 b0 = *(const f32x4*)(ln_b + g * HDIM + 8 * ch), b1 = *(const f32x4*)(ln_b + g * HDIM + 8 * ch + 4);
;         v4u o;
;         o[0] = cvt_pk_bf16((bf_lo(v[0]) - mean) * rstd * g0[0] + b0[0], (bf_hi(v[0]) - mean) * rstd * g0[1] + b0[1]);
;         o[1] = cvt_pk_bf16((bf_lo(v[1]) - mean) * rstd * g0[2] + b0[2], (bf_hi(v[1]) - mean) * rstd * g0[3] + b0[3]);
;         o[2] = cvt_pk_bf16((bf_lo(v[2]) - mean) * rstd * g1[0] + b1[0], (bf_hi(v[2]) - mean) * rstd * g1[1] + b1[1]);
;         o[3] = cvt_pk_bf16((bf_lo(v[3]) - mean) * rstd * g1[2] + b1[2], (bf_hi(v[3]) - mean) * rstd * g1[3] + b1[3]);
;         *(LAS v4u*)(TB + offb(r, ch)) = o; }
;     __syncthreads();
	ds_read_b64 v[0:1], v74
	ds_read_b64 v[2:3], v75
	ds_read_b64 v[4:5], v76
	ds_read_b64 v[6:7], v77
	s_waitcnt vmcnt(7)
	s_waitcnt lgkmcnt(3)
	v_lshlrev_b32_e32 v8, 16, v80
	v_and_b32_e32 v9, 0xffff0000, v80
	v_lshlrev_b32_e32 v10, 16, v81
	v_and_b32_e32 v11, 0xffff0000, v81
	v_pk_add_f32 v[8:9], v[8:9], v[0:1] op_sel_hi:[1,0] neg_lo:[0,1] neg_hi:[0,1]
	v_pk_add_f32 v[10:11], v[10:11], v[0:1] op_sel_hi:[1,0] neg_lo:[0,1] neg_hi:[0,1]
	v_pk_mul_f32 v[8:9], v[0:1], v[8:9] op_sel:[1,0]
	v_pk_mul_f32 v[10:11], v[0:1], v[10:11] op_sel:[1,0]
	v_pk_fma_f32 v[8:9], v[8:9], v[212:213], v[220:221]
	v_pk_fma_f32 v[10:11], v[10:11], v[214:215], v[222:223]
	v_cvt_pk_bf16_f32 v80, v8, v9
	v_cvt_pk_bf16_f32 v81, v10, v11
	v_lshlrev_b32_e32 v8, 16, v82
	v_and_b32_e32 v9, 0xffff0000, v82
	v_lshlrev_b32_e32 v10, 16, v83
	v_and_b32_e32 v11, 0xffff0000, v83
	v_pk_add_f32 v[8:9], v[8:9], v[0:1] op_sel_hi:[1,0] neg_lo:[0,1] neg_hi:[0,1]
	v_pk_add_f32 v[10:11], v[10:11], v[0:1] op_sel_hi:[1,0] neg_lo:[0,1] neg_hi:[0,1]
	v_pk_mul_f32 v[8:9], v[0:1], v[8:9] op_sel:[1,0]
	v_pk_mul_f32 v[10:11], v[0:1], v[10:11] op_sel:[1,0]
	v_pk_fma_f32 v[8:9], v[8:9], v[216:217], v[124:125]
	v_pk_fma_f32 v[10:11], v[10:11], v[218:219], v[126:127]
	v_cvt_pk_bf16_f32 v82, v8, v9
	v_cvt_pk_bf16_f32 v83, v10, v11
	ds_write_b128 v70, v[80:83] offset:34816
	s_waitcnt lgkmcnt(3)
	v_lshlrev_b32_e32 v8, 16, v84
	v_and_b32_e32 v9, 0xffff0000, v84
	v_lshlrev_b32_e32 v10, 16, v85
	v_and_b32_e32 v11, 0xffff0000, v85
	v_pk_add_f32 v[8:9], v[8:9], v[2:3] op_sel_hi:[1,0] neg_lo:[0,1] neg_hi:[0,1]
	v_pk_add_f32 v[10:11], v[10:11], v[2:3] op_sel_hi:[1,0] neg_lo:[0,1] neg_hi:[0,1]
	v_pk_mul_f32 v[8:9], v[2:3], v[8:9] op_sel:[1,0]
	v_pk_mul_f32 v[10:11], v[2:3], v[10:11] op_sel:[1,0]
	v_pk_fma_f32 v[8:9], v[8:9], v[212:213], v[220:221]
	v_pk_fma_f32 v[10:11], v[10:11], v[214:215], v[222:223]
	v_cvt_pk_bf16_f32 v84, v8, v9
	v_cvt_pk_bf16_f32 v85, v10, v11
	v_lshlrev_b32_e32 v8, 16, v86
	v_and_b32_e32 v9, 0xffff0000, v86
	v_lshlrev_b32_e32 v10, 16, v87
	v_and_b32_e32 v11, 0xffff0000, v87
	v_pk_add_f32 v[8:9], v[8:9], v[2:3] op_sel_hi:[1,0] neg_lo:[0,1] neg_hi:[0,1]
	v_pk_add_f32 v[10:11], v[10:11], v[2:3] op_sel_hi:[1,0] neg_lo:[0,1] neg_hi:[0,1]
	v_pk_mul_f32 v[8:9], v[2:3], v[8:9] op_sel:[1,0]
	v_pk_mul_f32 v[10:11], v[2:3], v[10:11] op_sel:[1,0]
	v_pk_fma_f32 v[8:9], v[8:9], v[216:217], v[124:125]
	v_pk_fma_f32 v[10:11], v[10:11], v[218:219], v[126:127]
	v_cvt_pk_bf16_f32 v86, v8, v9
	v_cvt_pk_bf16_f32 v87, v10, v11
	ds_write_b128 v71, v[84:87] offset:34816
	s_waitcnt lgkmcnt(3)
	v_lshlrev_b32_e32 v8, 16, v88
	v_and_b32_e32 v9, 0xffff0000, v88
	v_lshlrev_b32_e32 v10, 16, v89
	v_and_b32_e32 v11, 0xffff0000, v89
	v_pk_add_f32 v[8:9], v[8:9], v[4:5] op_sel_hi:[1,0] neg_lo:[0,1] neg_hi:[0,1]
	v_pk_add_f32 v[10:11], v[10:11], v[4:5] op_sel_hi:[1,0] neg_lo:[0,1] neg_hi:[0,1]
	v_pk_mul_f32 v[8:9], v[4:5], v[8:9] op_sel:[1,0]
	v_pk_mul_f32 v[10:11], v[4:5], v[10:11] op_sel:[1,0]
	v_pk_fma_f32 v[8:9], v[8:9], v[212:213], v[220:221]
	v_pk_fma_f32 v[10:11], v[10:11], v[214:215], v[222:223]
	v_cvt_pk_bf16_f32 v88, v8, v9
	v_cvt_pk_bf16_f32 v89, v10, v11
	v_lshlrev_b32_e32 v8, 16, v90
	v_and_b32_e32 v9, 0xffff0000, v90
	v_lshlrev_b32_e32 v10, 16, v91
	v_and_b32_e32 v11, 0xffff0000, v91
	v_pk_add_f32 v[8:9], v[8:9], v[4:5] op_sel_hi:[1,0] neg_lo:[0,1] neg_hi:[0,1]
	v_pk_add_f32 v[10:11], v[10:11], v[4:5] op_sel_hi:[1,0] neg_lo:[0,1] neg_hi:[0,1]
	v_pk_mul_f32 v[8:9], v[4:5], v[8:9] op_sel:[1,0]
	v_pk_mul_f32 v[10:11], v[4:5], v[10:11] op_sel:[1,0]
	v_pk_fma_f32 v[8:9], v[8:9], v[216:217], v[124:125]
	v_pk_fma_f32 v[10:11], v[10:11], v[218:219], v[126:127]
	v_cvt_pk_bf16_f32 v90, v8, v9
	v_cvt_pk_bf16_f32 v91, v10, v11
	ds_write_b128 v72, v[88:91] offset:34816
	s_waitcnt lgkmcnt(3)
	v_lshlrev_b32_e32 v8, 16, v92
	v_and_b32_e32 v9, 0xffff0000, v92
	v_lshlrev_b32_e32 v10, 16, v93
	v_and_b32_e32 v11, 0xffff0000, v93
	v_pk_add_f32 v[8:9], v[8:9], v[6:7] op_sel_hi:[1,0] neg_lo:[0,1] neg_hi:[0,1]
	v_pk_add_f32 v[10:11], v[10:11], v[6:7] op_sel_hi:[1,0] neg_lo:[0,1] neg_hi:[0,1]
	v_pk_mul_f32 v[8:9], v[6:7], v[8:9] op_sel:[1,0]
	v_pk_mul_f32 v[10:11], v[6:7], v[10:11] op_sel:[1,0]
	v_pk_fma_f32 v[8:9], v[8:9], v[212:213], v[220:221]
	v_pk_fma_f32 v[10:11], v[10:11], v[214:215], v[222:223]
	v_cvt_pk_bf16_f32 v92, v8, v9
	v_cvt_pk_bf16_f32 v93, v10, v11
	v_lshlrev_b32_e32 v8, 16, v94
	v_and_b32_e32 v9, 0xffff0000, v94
	v_lshlrev_b32_e32 v10, 16, v95
	v_and_b32_e32 v11, 0xffff0000, v95
	v_pk_add_f32 v[8:9], v[8:9], v[6:7] op_sel_hi:[1,0] neg_lo:[0,1] neg_hi:[0,1]
	v_pk_add_f32 v[10:11], v[10:11], v[6:7] op_sel_hi:[1,0] neg_lo:[0,1] neg_hi:[0,1]
	v_pk_mul_f32 v[8:9], v[6:7], v[8:9] op_sel:[1,0]
	v_pk_mul_f32 v[10:11], v[6:7], v[10:11] op_sel:[1,0]
	v_pk_fma_f32 v[8:9], v[8:9], v[216:217], v[124:125]
	v_pk_fma_f32 v[10:11], v[10:11], v[218:219], v[126:127]
	v_cvt_pk_bf16_f32 v94, v8, v9
	v_cvt_pk_bf16_f32 v95, v10, v11
	ds_write_b128 v73, v[92:95] offset:34816
	s_waitcnt lgkmcnt(0)
	s_barrier
; template <bool A_TR, bool B_TR>
; __device__ __forceinline__ void mm128(f32x4 (&acc)[8], ldsp TA, ldsp TB, int w, int lane) {
;     const ldsp ab = A_TR ? tr_base(TA, lane) + 32u * w : row_base(TA, lane) + 16u * TP * w;
;     const ldsp bb = B_TR ? tr_base(TB, lane) : row_base(TB, lane);
;     if (MM_SETPRIO) __builtin_amdgcn_s_setprio(1);
;     ...
;     bf16x8 a[4];
; #pragma unroll
;     for (int ks = 0; ks < 4; ++ks) a[ks] = A_TR ? frag_tr(ab, 0, ks) : frag_row(ab, 0, ks);
;     mm_pipe<MM_G, 0, 4, 0, 8>(acc, [&](int c, int ks) { return B_TR ? frag_tr(bb, c, ks) : frag_row(bb, c, ks); }, [&](int ks) { return a[ks]; });
;     ...
; #pragma unroll
;     for (int ks = 0; ks < 4; ++ks) {
;         const bf16x8 a = A_TR ? frag_tr(ab, 0, ks) : frag_row(ab, 0, ks);
; #pragma unroll
;         for (int c = 0; c < 8; ++c) {
;             const bf16x8 b = B_TR ? frag_tr(bb, c, ks) : frag_row(bb, c, ks);
;             acc[c] = __builtin_amdgcn_mfma_f32_16x16x32_bf16(b, a, acc[c], 0, 0, 0);
;         }
;     }
;     ...
;     if (MM_SETPRIO) __builtin_amdgcn_s_setprio(0);
; }
	s_setprio 1
	ds_read_b128 v[124:127], v61
	ds_read_b64_tr_b16 v[180:181], v64 offset:35904
	ds_read_b64_tr_b16 v[178:179], v64 offset:34816
	ds_read_b64_tr_b16 v[182:183], v64 offset:34848
	ds_read_b64_tr_b16 v[184:185], v64 offset:35936
	ds_read_b64_tr_b16 v[186:187], v64 offset:34880
	ds_read_b64_tr_b16 v[188:189], v64 offset:35968
	ds_read_b64_tr_b16 v[190:191], v64 offset:34912
	ds_read_b64_tr_b16 v[192:193], v64 offset:36000
	ds_read_b64_tr_b16 v[194:195], v64 offset:34944
	ds_read_b64_tr_b16 v[196:197], v64 offset:36032
	ds_read_b64_tr_b16 v[198:199], v64 offset:34976
	ds_read_b64_tr_b16 v[200:201], v64 offset:36064
	ds_read_b64_tr_b16 v[202:203], v64 offset:35008
	ds_read_b64_tr_b16 v[204:205], v64 offset:36096
	ds_read_b64_tr_b16 v[206:207], v64 offset:35040
	ds_read_b64_tr_b16 v[208:209], v64 offset:36128
	s_waitcnt lgkmcnt(14)
	v_mfma_f32_16x16x32_bf16 v[4:7], v[178:181], v[124:127], 0
	ds_read_b128 v[212:215], v61 offset:64
	s_waitcnt lgkmcnt(13)
	v_mfma_f32_16x16x32_bf16 v[8:11], v[182:185], v[124:127], 0
	ds_read_b64_tr_b16 v[216:217], v64 offset:43520
	ds_read_b64_tr_b16 v[218:219], v64 offset:44608
	s_waitcnt lgkmcnt(13)
	v_mfma_f32_16x16x32_bf16 v[80:83], v[186:189], v[124:127], 0
	ds_read_b64_tr_b16 v[220:221], v64 offset:43552
	ds_read_b64_tr_b16 v[222:223], v64 offset:44640
	s_waitcnt lgkmcnt(13)
	v_mfma_f32_16x16x32_bf16 v[84:87], v[190:193], v[124:127], 0
	ds_read_b64_tr_b16 v[178:179], v64 offset:43584
	ds_read_b64_tr_b16 v[180:181], v64 offset:44672
	s_waitcnt lgkmcnt(13)
	v_mfma_f32_16x16x32_bf16 v[88:91], v[194:197], v[124:127], 0
	ds_read_b64_tr_b16 v[182:183], v64 offset:43616
	ds_read_b64_tr_b16 v[184:185], v64 offset:44704
	s_waitcnt lgkmcnt(13)
	v_mfma_f32_16x16x32_bf16 v[92:95], v[198:201], v[124:127], 0
	ds_read_b64_tr_b16 v[186:187], v64 offset:43648
	ds_read_b64_tr_b16 v[188:189], v64 offset:44736
	s_waitcnt lgkmcnt(13)
	v_mfma_f32_16x16x32_bf16 v[96:99], v[202:205], v[124:127], 0
	ds_read_b64_tr_b16 v[190:191], v64 offset:43680
	ds_read_b64_tr_b16 v[192:193], v64 offset:44768
	s_waitcnt lgkmcnt(13)
	v_mfma_f32_16x16x32_bf16 v[0:3], v[206:209], v[124:127], 0
	ds_read_b64_tr_b16 v[194:195], v64 offset:43712
	ds_read_b64_tr_b16 v[196:197], v64 offset:44800
	ds_read_b64_tr_b16 v[198:199], v64 offset:43744
	ds_read_b64_tr_b16 v[200:201], v64 offset:44832
	s_waitcnt lgkmcnt(14)
	v_mfma_f32_16x16x32_bf16 v[4:7], v[216:219], v[212:215], v[4:7]
	ds_read_b128 v[202:205], v61 offset:128
	s_waitcnt lgkmcnt(13)
	v_mfma_f32_16x16x32_bf16 v[8:11], v[220:223], v[212:215], v[8:11]
	ds_read_b64_tr_b16 v[206:207], v64 offset:52224
	ds_read_b64_tr_b16 v[208:209], v64 offset:53312
	s_waitcnt lgkmcnt(13)
	v_mfma_f32_16x16x32_bf16 v[80:83], v[178:181], v[212:215], v[80:83]
	ds_read_b64_tr_b16 v[124:125], v64 offset:52256
	ds_read_b64_tr_b16 v[126:127], v64 offset:53344
	s_waitcnt lgkmcnt(13)
	v_mfma_f32_16x16x32_bf16 v[84:87], v[182:185], v[212:215], v[84:87]
	ds_read_b64_tr_b16 v[216:217], v64 offset:52288
	ds_read_b64_tr_b16 v[218:219], v64 offset:53376
	s_waitcnt lgkmcnt(13)
	v_mfma_f32_16x16x32_bf16 v[88:91], v[186:189], v[212:215], v[88:91]
	ds_read_b64_tr_b16 v[220:221], v64 offset:52320
	ds_read_b64_tr_b16 v[222:223], v64 offset:53408
	s_waitcnt lgkmcnt(13)
	v_mfma_f32_16x16x32_bf16 v[92:95], v[190:193], v[212:215], v[92:95]
	ds_read_b64_tr_b16 v[178:179], v64 offset:52352
	ds_read_b64_tr_b16 v[180:181], v64 offset:53440
	s_waitcnt lgkmcnt(13)
	v_mfma_f32_16x16x32_bf16 v[96:99], v[194:197], v[212:215], v[96:99]
	ds_read_b64_tr_b16 v[182:183], v64 offset:52384
	ds_read_b64_tr_b16 v[184:185], v64 offset:53472
	s_waitcnt lgkmcnt(13)
	v_mfma_f32_16x16x32_bf16 v[0:3], v[198:201], v[212:215], v[0:3]
	ds_read_b64_tr_b16 v[186:187], v64 offset:52416
	ds_read_b64_tr_b16 v[188:189], v64 offset:53504
	ds_read_b64_tr_b16 v[190:191], v64 offset:52448
	ds_read_b64_tr_b16 v[192:193], v64 offset:53536
	s_waitcnt lgkmcnt(14)
	v_mfma_f32_16x16x32_bf16 v[4:7], v[206:209], v[202:205], v[4:7]
	ds_read_b128 v[194:197], v61 offset:192
	s_waitcnt lgkmcnt(13)
	v_mfma_f32_16x16x32_bf16 v[8:11], v[124:127], v[202:205], v[8:11]
	ds_read_b64_tr_b16 v[198:199], v64 offset:60928
	ds_read_b64_tr_b16 v[200:201], v64 offset:62016
	s_waitcnt lgkmcnt(13)
	v_mfma_f32_16x16x32_bf16 v[80:83], v[216:219], v[202:205], v[80:83]
	ds_read_b64_tr_b16 v[212:213], v64 offset:60960
	ds_read_b64_tr_b16 v[214:215], v64 offset:62048
	s_waitcnt lgkmcnt(13)
	v_mfma_f32_16x16x32_bf16 v[84:87], v[220:223], v[202:205], v[84:87]
	ds_read_b64_tr_b16 v[206:207], v64 offset:60992
	ds_read_b64_tr_b16 v[208:209], v64 offset:62080
	s_waitcnt lgkmcnt(13)
	v_mfma_f32_16x16x32_bf16 v[88:91], v[178:181], v[202:205], v[88:91]
	ds_read_b64_tr_b16 v[124:125], v64 offset:61024
	ds_read_b64_tr_b16 v[126:127], v64 offset:62112
	s_waitcnt lgkmcnt(13)
	v_mfma_f32_16x16x32_bf16 v[92:95], v[182:185], v[202:205], v[92:95]
	ds_read_b64_tr_b16 v[216:217], v64 offset:61056
	ds_read_b64_tr_b16 v[218:219], v64 offset:62144
	s_waitcnt lgkmcnt(13)
	v_mfma_f32_16x16x32_bf16 v[96:99], v[186:189], v[202:205], v[96:99]
	ds_read_b64_tr_b16 v[220:221], v64 offset:61088
	ds_read_b64_tr_b16 v[222:223], v64 offset:62176
	s_waitcnt lgkmcnt(13)
	v_mfma_f32_16x16x32_bf16 v[0:3], v[190:193], v[202:205], v[0:3]
	ds_read_b64_tr_b16 v[178:179], v64 offset:61120
	ds_read_b64_tr_b16 v[180:181], v64 offset:62208
	ds_read_b64_tr_b16 v[182:183], v64 offset:61152
	ds_read_b64_tr_b16 v[184:185], v64 offset:62240
	s_waitcnt lgkmcnt(14)
	v_mfma_f32_16x16x32_bf16 v[4:7], v[198:201], v[194:197], v[4:7]
	s_waitcnt lgkmcnt(12)
	v_mfma_f32_16x16x32_bf16 v[8:11], v[212:215], v[194:197], v[8:11]
	s_waitcnt lgkmcnt(10)
; __device__ __forceinline__ unsigned cvt_pk_bf16(float lo, float hi) { const f32x2c_t v = {lo, hi}; return __builtin_bit_cast(unsigned, __builtin_convertvector(v, bf16x2c_t)); }
; #define LAS __attribute__((address_space(3)))
; #define LDS_WAIT() asm volatile("s_waitcnt lgkmcnt(0)" ::: "memory")
; __device__ __forceinline__ float bf_lo(unsigned w) { return __uint_as_float(w << 16); }
; __device__ __forceinline__ float bf_hi(unsigned w) { return __uint_as_float(w & 0xffff0000u); }
; __device__ __forceinline__ void sgu_unit(ldsp lds, const bf16* proj, bf16* mix, const float* sgup, const float* ln_g, const float* ln_b, const float* w_s, const float* b_s, int unit, int tid) {
;     ...
;     const int i = 16 * w + fr;
;     const float bs = b_s[g * CHUNK + i];
; #pragma unroll
;     for (int c = 0; c < 8; ++c) acc[c] = acc[c] + bs;
;     store_acc_tile(TA, acc, w, lane);
;     LDS_WAIT();
;     const bf16* ubase = proj + (row0 + 16 * w) * INW + C_U + g * HDIM;
;     bf16* obase = mix + (row0 + 16 * w) * DM + MIX_A + g * HDIM;
; #pragma unroll
;     for (int k = 0; k < 4; ++k) { const int q = lane + 64 * k, r = q >> 4, ch = q & 15;
;     ...
;         const v4u s = *(const LAS v4u*)(TA + offb(16 * w + r, ch)), u = ur[k];
;     ...
;         const v4u s = *(const LAS v4u*)(TA + offb(16 * w + r, ch)), u = *(const v4u*)(ubase + (size_t)r * INW + 8 * ch);
;     ...
;         v4u o;
; #pragma unroll
;         for (int e = 0; e < 4; ++e) o[e] = cvt_pk_bf16(bf_lo(u[e]) * bf_lo(s[e]), bf_hi(u[e]) * bf_hi(s[e]));
;         *(v4u*)(obase + (size_t)r * DM + 8 * ch) = o; }
	v_mfma_f32_16x16x32_bf16 v[80:83], v[206:209], v[194:197], v[80:83]
	s_waitcnt lgkmcnt(8)
	v_mfma_f32_16x16x32_bf16 v[84:87], v[124:127], v[194:197], v[84:87]
	s_waitcnt lgkmcnt(6)
	v_mfma_f32_16x16x32_bf16 v[88:91], v[216:219], v[194:197], v[88:91]
	s_waitcnt lgkmcnt(4)
	v_mfma_f32_16x16x32_bf16 v[92:95], v[220:223], v[194:197], v[92:95]
	s_waitcnt lgkmcnt(2)
	v_mfma_f32_16x16x32_bf16 v[96:99], v[178:181], v[194:197], v[96:99]
	s_waitcnt lgkmcnt(0)
	v_mfma_f32_16x16x32_bf16 v[0:3], v[182:185], v[194:197], v[0:3]
	s_nop 7
	s_setprio 0
	s_waitcnt vmcnt(0)
	v_pk_add_f32 v[6:7], v[6:7], v[110:111] op_sel_hi:[1,0]
	v_pk_add_f32 v[4:5], v[4:5], v[110:111] op_sel_hi:[1,0]
	v_pk_add_f32 v[10:11], v[10:11], v[110:111] op_sel_hi:[1,0]
	v_pk_add_f32 v[8:9], v[8:9], v[110:111] op_sel_hi:[1,0]
	v_pk_add_f32 v[82:83], v[82:83], v[110:111] op_sel_hi:[1,0]
	v_pk_add_f32 v[80:81], v[80:81], v[110:111] op_sel_hi:[1,0]
	v_pk_add_f32 v[86:87], v[86:87], v[110:111] op_sel_hi:[1,0]
	v_pk_add_f32 v[84:85], v[84:85], v[110:111] op_sel_hi:[1,0]
	v_pk_add_f32 v[90:91], v[90:91], v[110:111] op_sel_hi:[1,0]
	v_pk_add_f32 v[88:89], v[88:89], v[110:111] op_sel_hi:[1,0]
	v_pk_add_f32 v[94:95], v[94:95], v[110:111] op_sel_hi:[1,0]
	v_pk_add_f32 v[92:93], v[92:93], v[110:111] op_sel_hi:[1,0]
	v_pk_add_f32 v[98:99], v[98:99], v[110:111] op_sel_hi:[1,0]
	v_pk_add_f32 v[96:97], v[96:97], v[110:111] op_sel_hi:[1,0]
	v_pk_add_f32 v[2:3], v[2:3], v[110:111] op_sel_hi:[1,0]
	v_pk_add_f32 v[0:1], v[0:1], v[110:111] op_sel_hi:[1,0]
	v_or_b32_e32 v178, s24, v62
	v_mad_u64_u32 v[178:179], vcc, v178, s47, v[42:43]
	s_lshl_b64 s[12:13], s[12:13], 13
	s_add_u32 s4, s60, s12
	s_addc_u32 s5, s61, s13
	s_lshl_b32 s25, s0, 8
	s_add_u32 s4, s4, s25
	s_addc_u32 s5, s5, 0
	v_cvt_pk_bf16_f32 v4, v4, v5
	v_cvt_pk_bf16_f32 v5, v6, v7
	v_cvt_pk_bf16_f32 v6, v8, v9
	v_cvt_pk_bf16_f32 v7, v10, v11
	ds_write2_b64 v178, v[4:5], v[6:7] offset1:4
	v_cvt_pk_bf16_f32 v8, v80, v81
	v_cvt_pk_bf16_f32 v9, v82, v83
	v_cvt_pk_bf16_f32 v10, v84, v85
	v_cvt_pk_bf16_f32 v11, v86, v87
	ds_write2_b64 v178, v[8:9], v[10:11] offset0:8 offset1:12
	v_cvt_pk_bf16_f32 v4, v88, v89
	v_cvt_pk_bf16_f32 v5, v90, v91
	v_cvt_pk_bf16_f32 v6, v92, v93
	v_cvt_pk_bf16_f32 v7, v94, v95
	ds_write2_b64 v178, v[4:5], v[6:7] offset0:16 offset1:20
	v_cvt_pk_bf16_f32 v8, v96, v97
	v_cvt_pk_bf16_f32 v9, v98, v99
	v_cvt_pk_bf16_f32 v0, v0, v1
	v_cvt_pk_bf16_f32 v1, v2, v3
	v_mov_b32_e32 v61, 0
	ds_write2_b64 v178, v[8:9], v[0:1] offset0:24 offset1:28
	v_lshl_add_u64 v[196:197], s[4:5], 0, v[60:61]
	s_waitcnt lgkmcnt(0)
	v_or_b32_e32 v198, s24, v65
	v_mad_u64_u32 v[198:199], vcc, v198, s47, v[20:21]
	ds_read_b128 v[180:183], v198
	v_or_b32_e32 v200, s24, v66
	v_mad_u64_u32 v[200:201], vcc, v200, s47, v[20:21]
	ds_read_b128 v[184:187], v200
	v_or_b32_e32 v202, s24, v67
	v_mad_u64_u32 v[202:203], vcc, v202, s47, v[20:21]
	ds_read_b128 v[188:191], v202
	v_or_b32_e32 v204, s24, v68
	v_mad_u64_u32 v[204:205], vcc, v204, s47, v[20:21]
	ds_read_b128 v[192:195], v204
	s_waitcnt lgkmcnt(3)
	v_lshlrev_b32_e32 v200, 16, v180
	v_and_b32_e32 v201, 0xffff0000, v180
	v_lshlrev_b32_e32 v202, 16, v100
	v_and_b32_e32 v203, 0xffff0000, v100
	v_lshlrev_b32_e32 v204, 16, v181
	v_and_b32_e32 v205, 0xffff0000, v181
	v_lshlrev_b32_e32 v206, 16, v101
	v_and_b32_e32 v207, 0xffff0000, v101
	v_pk_mul_f32 v[202:203], v[200:201], v[202:203]
	v_pk_mul_f32 v[206:207], v[204:205], v[206:207]
	v_lshl_add_u64 v[208:209], v[196:197], 0, v[46:47]
	v_cvt_pk_bf16_f32 v4, v202, v203
	v_cvt_pk_bf16_f32 v5, v206, v207
	v_lshlrev_b32_e32 v200, 16, v182
	v_and_b32_e32 v201, 0xffff0000, v182
	v_lshlrev_b32_e32 v202, 16, v102
	v_and_b32_e32 v203, 0xffff0000, v102
	v_lshlrev_b32_e32 v204, 16, v183
	v_and_b32_e32 v205, 0xffff0000, v183
	v_lshlrev_b32_e32 v206, 16, v103
	v_and_b32_e32 v207, 0xffff0000, v103
	v_pk_mul_f32 v[202:203], v[200:201], v[202:203]
	v_pk_mul_f32 v[206:207], v[204:205], v[206:207]
	v_lshl_add_u64 v[208:209], v[196:197], 0, v[46:47]
	v_cvt_pk_bf16_f32 v6, v202, v203
	v_cvt_pk_bf16_f32 v7, v206, v207
	global_store_dwordx4 v[208:209], v[4:7], off
	s_waitcnt lgkmcnt(2)
; __device__ __forceinline__ unsigned cvt_pk_bf16(float lo, float hi) { const f32x2c_t v = {lo, hi}; return __builtin_bit_cast(unsigned, __builtin_convertvector(v, bf16x2c_t)); }
; #define LAS __attribute__((address_space(3)))
; __device__ __forceinline__ float bf_lo(unsigned w) { return __uint_as_float(w << 16); }
; __device__ __forceinline__ float bf_hi(unsigned w) { return __uint_as_float(w & 0xffff0000u); }
; __device__ __forceinline__ void sgu_unit(ldsp lds, const bf16* proj, bf16* mix, const float* sgup, const float* ln_g, const float* ln_b, const float* w_s, const float* b_s, int unit, int tid) {
;     ...
;     for (int k = 0; k < 4; ++k) { const int q = lane + 64 * k, r = q >> 4, ch = q & 15;
;     ...
;         const v4u s = *(const LAS v4u*)(TA + offb(16 * w + r, ch)), u = ur[k];
;     ...
;         const v4u s = *(const LAS v4u*)(TA + offb(16 * w + r, ch)), u = *(const v4u*)(ubase + (size_t)r * INW + 8 * ch);
;     ...
;         v4u o;
; #pragma unroll
;         for (int e = 0; e < 4; ++e) o[e] = cvt_pk_bf16(bf_lo(u[e]) * bf_lo(s[e]), bf_hi(u[e]) * bf_hi(s[e]));
;         *(v4u*)(obase + (size_t)r * DM + 8 * ch) = o; }
	v_lshlrev_b32_e32 v200, 16, v184
	v_and_b32_e32 v201, 0xffff0000, v184
	v_lshlrev_b32_e32 v202, 16, v236
	v_and_b32_e32 v203, 0xffff0000, v236
	v_lshlrev_b32_e32 v204, 16, v185
	v_and_b32_e32 v205, 0xffff0000, v185
	v_lshlrev_b32_e32 v206, 16, v237
	v_and_b32_e32 v207, 0xffff0000, v237
	v_pk_mul_f32 v[202:203], v[200:201], v[202:203]
	v_pk_mul_f32 v[206:207], v[204:205], v[206:207]
	v_lshl_add_u64 v[212:213], v[196:197], 0, v[50:51]
	v_cvt_pk_bf16_f32 v80, v202, v203
	v_cvt_pk_bf16_f32 v81, v206, v207
	v_lshlrev_b32_e32 v200, 16, v186
	v_and_b32_e32 v201, 0xffff0000, v186
	v_lshlrev_b32_e32 v202, 16, v238
	v_and_b32_e32 v203, 0xffff0000, v238
	v_lshlrev_b32_e32 v204, 16, v187
	v_and_b32_e32 v205, 0xffff0000, v187
	v_lshlrev_b32_e32 v206, 16, v239
	v_and_b32_e32 v207, 0xffff0000, v239
	v_pk_mul_f32 v[202:203], v[200:201], v[202:203]
	v_pk_mul_f32 v[206:207], v[204:205], v[206:207]
	v_lshl_add_u64 v[212:213], v[196:197], 0, v[50:51]
	v_cvt_pk_bf16_f32 v82, v202, v203
	v_cvt_pk_bf16_f32 v83, v206, v207
	global_store_dwordx4 v[212:213], v[80:83], off
	s_waitcnt lgkmcnt(1)
	v_lshlrev_b32_e32 v200, 16, v188
	v_and_b32_e32 v201, 0xffff0000, v188
	v_lshlrev_b32_e32 v202, 16, v224
	v_and_b32_e32 v203, 0xffff0000, v224
	v_lshlrev_b32_e32 v204, 16, v189
	v_and_b32_e32 v205, 0xffff0000, v189
	v_lshlrev_b32_e32 v206, 16, v225
	v_and_b32_e32 v207, 0xffff0000, v225
	v_pk_mul_f32 v[202:203], v[200:201], v[202:203]
	v_pk_mul_f32 v[206:207], v[204:205], v[206:207]
	v_lshl_add_u64 v[208:209], v[196:197], 0, v[54:55]
	v_cvt_pk_bf16_f32 v4, v202, v203
	v_cvt_pk_bf16_f32 v5, v206, v207
	v_lshlrev_b32_e32 v200, 16, v190
	v_and_b32_e32 v201, 0xffff0000, v190
	v_lshlrev_b32_e32 v202, 16, v242
	v_and_b32_e32 v203, 0xffff0000, v242
	v_lshlrev_b32_e32 v204, 16, v191
	v_and_b32_e32 v205, 0xffff0000, v191
	v_lshlrev_b32_e32 v206, 16, v243
	v_and_b32_e32 v207, 0xffff0000, v243
	v_pk_mul_f32 v[202:203], v[200:201], v[202:203]
	v_pk_mul_f32 v[206:207], v[204:205], v[206:207]
	v_lshl_add_u64 v[208:209], v[196:197], 0, v[54:55]
	v_cvt_pk_bf16_f32 v6, v202, v203
	v_cvt_pk_bf16_f32 v7, v206, v207
	global_store_dwordx4 v[208:209], v[4:7], off
	s_waitcnt lgkmcnt(0)
	v_lshlrev_b32_e32 v200, 16, v192
	v_and_b32_e32 v201, 0xffff0000, v192
	v_lshlrev_b32_e32 v202, 16, v246
	v_and_b32_e32 v203, 0xffff0000, v246
	v_lshlrev_b32_e32 v204, 16, v193
	v_and_b32_e32 v205, 0xffff0000, v193
	v_lshlrev_b32_e32 v206, 16, v247
	v_and_b32_e32 v207, 0xffff0000, v247
	v_pk_mul_f32 v[202:203], v[200:201], v[202:203]
	v_pk_mul_f32 v[206:207], v[204:205], v[206:207]
	v_lshl_add_u64 v[212:213], v[196:197], 0, v[58:59]
	v_cvt_pk_bf16_f32 v80, v202, v203
	v_cvt_pk_bf16_f32 v81, v206, v207
	v_lshlrev_b32_e32 v200, 16, v194
	v_and_b32_e32 v201, 0xffff0000, v194
	v_lshlrev_b32_e32 v202, 16, v250
	v_and_b32_e32 v203, 0xffff0000, v250
	v_lshlrev_b32_e32 v204, 16, v195
	v_and_b32_e32 v205, 0xffff0000, v195
	v_lshlrev_b32_e32 v206, 16, v251
	v_and_b32_e32 v207, 0xffff0000, v251
	v_pk_mul_f32 v[202:203], v[200:201], v[202:203]
	v_pk_mul_f32 v[206:207], v[204:205], v[206:207]
	v_lshl_add_u64 v[212:213], v[196:197], 0, v[58:59]
	v_cvt_pk_bf16_f32 v82, v202, v203
	v_cvt_pk_bf16_f32 v83, v206, v207
	global_store_dwordx4 v[212:213], v[80:83], off
	s_and_saveexec_b64 s[0:1], s[6:7]
	s_cbranch_execz .LBB0_397
	v_mov_b32_e32 v0, s46
	ds_write_b32 v0, v78
	s_branch .LBB0_397
